# nt hint on the rmsnorm passes' f32 residual-row loads (single-use stream; keeps bf16 operands resident)
# speedup vs baseline: 1.0146x; 1.0006x over previous
; __device__ __forceinline__ float wave_sum(float v) {
; #pragma unroll
;     for (int o = 1; o < 64; o <<= 1) v += __shfl_xor(v, o);
;     return v;
; __device__ __forceinline__ void rms_rows(const Ctx& C, const float* __restrict__ x, const float* __restrict__ w, bf16_t* __restrict__ o) {
;     ...
;     for (int row = C.gw; row < T; row += C.ngw) {
;         const f32x4* xr = (const f32x4*)(x + (size_t)row * DM) + C.lane; f32x4 v[8]; float s = 0.f;
; #pragma unroll
;         for (int j = 0; j < 8; ++j) { v[j] = xr[64 * j]; s += (v[j].x * v[j].x + v[j].y * v[j].y) + (v[j].z * v[j].z + v[j].w * v[j].w); }
;         const float r = rsqrtf(wave_sum(s) * (1.f / DM) + 1e-6f);
.LBB0_80:
	global_load_dwordx4 v[38:41], v[68:69], off offset:-4096 nt
	global_load_dwordx4 v[34:37], v[68:69], off offset:-3072 nt
	s_ashr_i32 s3, s14, 3
	s_andn2_b32 s3, s3, 31
	s_and_b32 s4, s17, 0x3fc0
	s_lshl_b32 s86, s4, 1
	s_add_i32 s14, s14, s6
	s_add_i32 s17, s17, s2
	s_cmpk_gt_i32 s14, 0x3fff
	s_waitcnt vmcnt(1)
	v_mov_b32_e32 v44, v39
	s_waitcnt vmcnt(0)
	v_mov_b32_e32 v45, v35
	v_mov_b32_e32 v42, v38
	v_mov_b32_e32 v43, v34
	v_pk_mul_f32 v[44:45], v[44:45], v[44:45]
	v_mov_b32_e32 v46, v41
	v_mov_b32_e32 v47, v37
	v_pk_fma_f32 v[42:43], v[42:43], v[42:43], v[44:45]
	v_mov_b32_e32 v44, v40
	v_mov_b32_e32 v45, v36
	v_pk_mul_f32 v[46:47], v[46:47], v[46:47]
	s_nop 0
	v_pk_fma_f32 v[44:45], v[44:45], v[44:45], v[46:47]
	global_load_dwordx4 v[46:49], v[68:69], off offset:-2048 nt
	v_pk_add_f32 v[54:55], v[42:43], v[44:45]
	s_waitcnt vmcnt(0)
	v_pk_mul_f32 v[42:43], v[48:49], v[48:49]
	v_pk_mul_f32 v[44:45], v[46:47], v[46:47]
	v_pk_add_f32 v[54:55], v[54:55], v[54:55] op_sel:[0,1] op_sel_hi:[1,0]
	v_pk_mov_b32 v[50:51], v[44:45], v[42:43] op_sel:[1,0]
	v_mov_b32_e32 v45, v43
	v_pk_add_f32 v[56:57], v[50:51], v[44:45]
	global_load_dwordx4 v[42:45], v[68:69], off offset:-1024 nt
	global_load_dwordx4 v[50:53], v[68:69], off nt
	v_pk_add_f32 v[56:57], v[56:57], v[56:57] op_sel:[0,1] op_sel_hi:[1,0]
	s_waitcnt vmcnt(0)
	v_mul_f32_e32 v0, v50, v50
	v_mul_f32_e32 v58, v51, v51
	v_mov_b32_e32 v55, v0
	v_mov_b32_e32 v57, v58
	v_mul_f32_e32 v0, v43, v43
	v_mul_f32_e32 v59, v52, v52
	v_pk_add_f32 v[54:55], v[54:55], v[56:57]
	v_pk_fma_f32 v[56:57], v[42:43], v[42:43], v[0:1] op_sel_hi:[1,1,0]
	v_mul_f32_e32 v0, v45, v45
	v_mul_f32_e32 v60, v53, v53
	v_mov_b32_e32 v57, v59
	v_pk_fma_f32 v[58:59], v[44:45], v[44:45], v[0:1] op_sel_hi:[1,1,0]
	s_nop 0
	v_mov_b32_e32 v59, v60
	v_pk_add_f32 v[56:57], v[56:57], v[58:59]
	global_load_dwordx4 v[58:61], v[68:69], off offset:1024 nt
	v_pk_add_f32 v[78:79], v[54:55], v[56:57]
	s_waitcnt vmcnt(0)
	v_pk_mul_f32 v[54:55], v[60:61], v[60:61]
	v_pk_mul_f32 v[56:57], v[58:59], v[58:59]
	v_pk_add_f32 v[78:79], v[78:79], v[78:79] op_sel:[0,1] op_sel_hi:[1,0]
	v_pk_mov_b32 v[62:63], v[56:57], v[54:55] op_sel:[1,0]
	v_mov_b32_e32 v57, v55
	v_pk_add_f32 v[80:81], v[62:63], v[56:57]
	global_load_dwordx4 v[54:57], v[68:69], off offset:2048 nt
	global_load_dwordx4 v[62:65], v[68:69], off offset:3072 nt
	v_pk_add_f32 v[80:81], v[80:81], v[80:81] op_sel:[0,1] op_sel_hi:[1,0]
	v_lshl_add_u64 v[68:69], v[68:69], 0, s[0:1]
	s_waitcnt vmcnt(0)
	v_mul_f32_e32 v0, v62, v62
	v_mul_f32_e32 v77, v63, v63
	v_mov_b32_e32 v79, v0
	v_mov_b32_e32 v81, v77
	v_mul_f32_e32 v0, v55, v55
	v_mul_f32_e32 v82, v64, v64
	v_pk_add_f32 v[78:79], v[78:79], v[80:81]
	v_pk_fma_f32 v[80:81], v[54:55], v[54:55], v[0:1] op_sel_hi:[1,1,0]
	v_mul_f32_e32 v0, v57, v57
	v_mul_f32_e32 v84, v65, v65
	v_mov_b32_e32 v81, v82
	v_pk_fma_f32 v[82:83], v[56:57], v[56:57], v[0:1] op_sel_hi:[1,1,0]
	s_nop 0
	v_mov_b32_e32 v83, v84
	v_pk_add_f32 v[80:81], v[80:81], v[82:83]
	s_nop 0
	v_pk_add_f32 v[78:79], v[78:79], v[80:81]
	s_nop 0
	v_add_f32_e32 v0, v78, v79
	ds_bpermute_b32 v77, v70, v0
	v_lshl_add_u64 v[78:79], v[66:67], 0, s[86:87]
	s_waitcnt lgkmcnt(0)
	v_add_f32_e32 v0, v0, v77
	ds_bpermute_b32 v77, v71, v0
	s_waitcnt lgkmcnt(0)
	v_add_f32_e32 v0, v0, v77
	ds_bpermute_b32 v77, v72, v0
	s_waitcnt lgkmcnt(0)
	v_add_f32_e32 v0, v0, v77
	ds_bpermute_b32 v77, v73, v0
	s_waitcnt lgkmcnt(0)
	v_add_f32_e32 v0, v0, v77
	ds_bpermute_b32 v77, v74, v0
	s_waitcnt lgkmcnt(0)
	v_add_f32_e32 v0, v0, v77
	ds_bpermute_b32 v77, v75, v0
	s_waitcnt lgkmcnt(0)
; __device__ __forceinline__ unsigned pk2(float lo, float hi) { f32x2 v = {lo, hi}; bf16x2_t b = __builtin_convertvector(v, bf16x2_t); return __builtin_bit_cast(unsigned, b); }
; __device__ __forceinline__ void rms_rows(const Ctx& C, const float* __restrict__ x, const float* __restrict__ w, bf16_t* __restrict__ o) {
;     ...
;         const float r = rsqrtf(wave_sum(s) * (1.f / DM) + 1e-6f);
; #pragma unroll
;         for (int j = 0; j < 8; ++j) { u32x2 q; q.x = pk2(v[j].x * r * wv[j].x, v[j].y * r * wv[j].y); q.y = pk2(v[j].z * r * wv[j].z, v[j].w * r * wv[j].w);
;             const int col = 4 * (C.lane + 64 * j);
;             *(u32x2*)(o + ((size_t)((row >> 8) * (DM / 64) + (col >> 6)) * 256 + (row & 255)) * 64 + (col & 63)) = q; }
	v_add_f32_e32 v0, v0, v77
	v_fmamk_f32 v0, v0, 0x3a000000, v196
	v_cmp_gt_f32_e32 vcc, s85, v0
	v_mul_f32_e32 v77, 0x4b800000, v0
	s_nop 0
	v_cndmask_b32_e32 v0, v0, v77, vcc
	v_rsq_f32_e32 v0, v0
	s_nop 0
	v_mul_f32_e32 v77, 0x45800000, v0
	v_cndmask_b32_e32 v0, v0, v77, vcc
	v_pk_mul_f32 v[38:39], v[38:39], v[0:1] op_sel_hi:[1,0]
	v_pk_mul_f32 v[40:41], v[40:41], v[0:1] op_sel_hi:[1,0]
	v_pk_mul_f32 v[38:39], v[30:31], v[38:39]
	v_pk_mul_f32 v[40:41], v[32:33], v[40:41]
	v_pk_mul_f32 v[34:35], v[34:35], v[0:1] op_sel_hi:[1,0]
	v_pk_mul_f32 v[36:37], v[36:37], v[0:1] op_sel_hi:[1,0]
	v_cvt_pk_bf16_f32 v38, v38, v39
	v_cvt_pk_bf16_f32 v39, v40, v41
	v_or_b32_e32 v40, s3, v76
	v_pk_mul_f32 v[34:35], v[26:27], v[34:35]
	v_pk_mul_f32 v[36:37], v[28:29], v[36:37]
	v_cvt_pk_bf16_f32 v34, v34, v35
	v_cvt_pk_bf16_f32 v35, v36, v37
	v_or_b32_e32 v36, 4, v40
	v_ashrrev_i32_e32 v37, 31, v36
	v_lshlrev_b64 v[36:37], 15, v[36:37]
	v_lshl_add_u64 v[36:37], v[78:79], 0, v[36:37]
	global_store_dwordx2 v[36:37], v[34:35], off
	v_pk_mul_f32 v[34:35], v[46:47], v[0:1] op_sel_hi:[1,0]
	v_pk_mul_f32 v[36:37], v[48:49], v[0:1] op_sel_hi:[1,0]
	v_pk_mul_f32 v[34:35], v[22:23], v[34:35]
	v_pk_mul_f32 v[36:37], v[24:25], v[36:37]
	v_cvt_pk_bf16_f32 v34, v34, v35
	v_cvt_pk_bf16_f32 v35, v36, v37
	v_or_b32_e32 v36, 8, v40
	v_ashrrev_i32_e32 v37, 31, v36
	v_lshlrev_b64 v[36:37], 15, v[36:37]
	v_lshl_add_u64 v[36:37], v[78:79], 0, v[36:37]
	global_store_dwordx2 v[36:37], v[34:35], off
	v_pk_mul_f32 v[34:35], v[42:43], v[0:1] op_sel_hi:[1,0]
	v_pk_mul_f32 v[36:37], v[44:45], v[0:1] op_sel_hi:[1,0]
	v_pk_mul_f32 v[34:35], v[18:19], v[34:35]
	v_pk_mul_f32 v[36:37], v[20:21], v[36:37]
	v_cvt_pk_bf16_f32 v34, v34, v35
	v_cvt_pk_bf16_f32 v35, v36, v37
	v_or_b32_e32 v36, 12, v40
	v_ashrrev_i32_e32 v37, 31, v36
	v_lshlrev_b64 v[36:37], 15, v[36:37]
	v_lshl_add_u64 v[36:37], v[78:79], 0, v[36:37]
	global_store_dwordx2 v[36:37], v[34:35], off
	v_pk_mul_f32 v[34:35], v[50:51], v[0:1] op_sel_hi:[1,0]
	v_pk_mul_f32 v[36:37], v[52:53], v[0:1] op_sel_hi:[1,0]
	v_pk_mul_f32 v[34:35], v[14:15], v[34:35]
	v_pk_mul_f32 v[36:37], v[16:17], v[36:37]
	v_cvt_pk_bf16_f32 v34, v34, v35
	v_cvt_pk_bf16_f32 v35, v36, v37
	v_or_b32_e32 v36, 16, v40
	v_ashrrev_i32_e32 v37, 31, v36
	v_lshlrev_b64 v[36:37], 15, v[36:37]
	v_lshl_add_u64 v[36:37], v[78:79], 0, v[36:37]
	global_store_dwordx2 v[36:37], v[34:35], off
	v_pk_mul_f32 v[34:35], v[58:59], v[0:1] op_sel_hi:[1,0]
	v_pk_mul_f32 v[36:37], v[60:61], v[0:1] op_sel_hi:[1,0]
	v_pk_mul_f32 v[34:35], v[10:11], v[34:35]
	v_pk_mul_f32 v[36:37], v[12:13], v[36:37]
	v_cvt_pk_bf16_f32 v34, v34, v35
	v_cvt_pk_bf16_f32 v35, v36, v37
	v_or_b32_e32 v36, 20, v40
	v_ashrrev_i32_e32 v37, 31, v36
	v_lshlrev_b64 v[36:37], 15, v[36:37]
	v_lshl_add_u64 v[36:37], v[78:79], 0, v[36:37]
	global_store_dwordx2 v[36:37], v[34:35], off
	v_pk_mul_f32 v[34:35], v[54:55], v[0:1] op_sel_hi:[1,0]
	v_pk_mul_f32 v[36:37], v[56:57], v[0:1] op_sel_hi:[1,0]
	v_pk_mul_f32 v[34:35], v[6:7], v[34:35]
	v_pk_mul_f32 v[36:37], v[8:9], v[36:37]
	v_cvt_pk_bf16_f32 v34, v34, v35
	v_cvt_pk_bf16_f32 v35, v36, v37
	v_or_b32_e32 v36, 24, v40
	v_ashrrev_i32_e32 v37, 31, v36
	v_lshlrev_b64 v[36:37], 15, v[36:37]
	v_lshl_add_u64 v[36:37], v[78:79], 0, v[36:37]
	global_store_dwordx2 v[36:37], v[34:35], off
	v_pk_mul_f32 v[34:35], v[62:63], v[0:1] op_sel_hi:[1,0]
	v_pk_mul_f32 v[36:37], v[64:65], v[0:1] op_sel_hi:[1,0]
	v_pk_mul_f32 v[34:35], v[2:3], v[34:35]
	v_pk_mul_f32 v[36:37], v[4:5], v[36:37]
	v_cvt_pk_bf16_f32 v34, v34, v35
	v_cvt_pk_bf16_f32 v35, v36, v37
	v_or_b32_e32 v36, 28, v40
	v_ashrrev_i32_e32 v41, 31, v40
	v_ashrrev_i32_e32 v37, 31, v36
	v_lshlrev_b64 v[80:81], 15, v[40:41]
	v_lshlrev_b64 v[36:37], 15, v[36:37]
	v_lshl_add_u64 v[80:81], v[78:79], 0, v[80:81]
	v_lshl_add_u64 v[36:37], v[78:79], 0, v[36:37]
	global_store_dwordx2 v[80:81], v[38:39], off
	global_store_dwordx2 v[36:37], v[34:35], off
	s_cbranch_scc0 .LBB0_80

; __device__ __forceinline__ float wave_sum(float v) {
; #pragma unroll
;     for (int o = 1; o < 64; o <<= 1) v += __shfl_xor(v, o);
;     return v;
; __device__ __forceinline__ void rms_rows(const Ctx& C, const float* __restrict__ x, const float* __restrict__ w, bf16_t* __restrict__ o) {
;     ...
;     for (int row = C.gw; row < T; row += C.ngw) {
;         const f32x4* xr = (const f32x4*)(x + (size_t)row * DM) + C.lane; f32x4 v[8]; float s = 0.f;
; #pragma unroll
;         for (int j = 0; j < 8; ++j) { v[j] = xr[64 * j]; s += (v[j].x * v[j].x + v[j].y * v[j].y) + (v[j].z * v[j].z + v[j].w * v[j].w); }
;         const float r = rsqrtf(wave_sum(s) * (1.f / DM) + 1e-6f);
.LBB0_1030:
	global_load_dwordx4 v[38:41], v[68:69], off offset:-4096 nt
	global_load_dwordx4 v[34:37], v[68:69], off offset:-3072 nt
	s_ashr_i32 s1, s12, 3
	s_andn2_b32 s1, s1, 31
	s_and_b32 s6, s4, 0x3fc0
	s_lshl_b32 s86, s6, 1
	s_add_i32 s12, s12, s0
	s_add_i32 s4, s4, s5
	s_cmpk_lt_i32 s12, 0x4000
	s_waitcnt vmcnt(1)
	v_mov_b32_e32 v44, v39
	s_waitcnt vmcnt(0)
	v_mov_b32_e32 v45, v35
	v_mov_b32_e32 v42, v38
	v_mov_b32_e32 v43, v34
	v_pk_mul_f32 v[44:45], v[44:45], v[44:45]
	v_mov_b32_e32 v46, v41
	v_mov_b32_e32 v47, v37
	v_pk_fma_f32 v[42:43], v[42:43], v[42:43], v[44:45]
	v_mov_b32_e32 v44, v40
	v_mov_b32_e32 v45, v36
	v_pk_mul_f32 v[46:47], v[46:47], v[46:47]
	s_nop 0
	v_pk_fma_f32 v[44:45], v[44:45], v[44:45], v[46:47]
	global_load_dwordx4 v[46:49], v[68:69], off offset:-2048 nt
	v_pk_add_f32 v[54:55], v[42:43], v[44:45]
	s_waitcnt vmcnt(0)
	v_pk_mul_f32 v[42:43], v[48:49], v[48:49]
	v_pk_mul_f32 v[44:45], v[46:47], v[46:47]
	v_pk_add_f32 v[54:55], v[54:55], v[54:55] op_sel:[0,1] op_sel_hi:[1,0]
	v_pk_mov_b32 v[50:51], v[44:45], v[42:43] op_sel:[1,0]
	v_mov_b32_e32 v45, v43
	v_pk_add_f32 v[56:57], v[50:51], v[44:45]
	global_load_dwordx4 v[42:45], v[68:69], off offset:-1024 nt
	global_load_dwordx4 v[50:53], v[68:69], off nt
	v_pk_add_f32 v[56:57], v[56:57], v[56:57] op_sel:[0,1] op_sel_hi:[1,0]
	s_waitcnt vmcnt(0)
	v_mul_f32_e32 v0, v50, v50
	v_mul_f32_e32 v58, v51, v51
	v_mov_b32_e32 v55, v0
	v_mov_b32_e32 v57, v58
	v_mul_f32_e32 v0, v43, v43
	v_mul_f32_e32 v59, v52, v52
	v_pk_add_f32 v[54:55], v[54:55], v[56:57]
	v_pk_fma_f32 v[56:57], v[42:43], v[42:43], v[0:1] op_sel_hi:[1,1,0]
	v_mul_f32_e32 v0, v45, v45
	v_mul_f32_e32 v60, v53, v53
	v_mov_b32_e32 v57, v59
	v_pk_fma_f32 v[58:59], v[44:45], v[44:45], v[0:1] op_sel_hi:[1,1,0]
	s_nop 0
	v_mov_b32_e32 v59, v60
	v_pk_add_f32 v[56:57], v[56:57], v[58:59]
	global_load_dwordx4 v[58:61], v[68:69], off offset:1024 nt
	v_pk_add_f32 v[78:79], v[54:55], v[56:57]
	s_waitcnt vmcnt(0)
	v_pk_mul_f32 v[54:55], v[60:61], v[60:61]
	v_pk_mul_f32 v[56:57], v[58:59], v[58:59]
	v_pk_add_f32 v[78:79], v[78:79], v[78:79] op_sel:[0,1] op_sel_hi:[1,0]
	v_pk_mov_b32 v[62:63], v[56:57], v[54:55] op_sel:[1,0]
	v_mov_b32_e32 v57, v55
	v_pk_add_f32 v[80:81], v[62:63], v[56:57]
	global_load_dwordx4 v[54:57], v[68:69], off offset:2048 nt
	global_load_dwordx4 v[62:65], v[68:69], off offset:3072 nt
	v_pk_add_f32 v[80:81], v[80:81], v[80:81] op_sel:[0,1] op_sel_hi:[1,0]
	v_lshl_add_u64 v[68:69], v[68:69], 0, s[2:3]
	s_waitcnt vmcnt(0)
	v_mul_f32_e32 v0, v62, v62
	v_mul_f32_e32 v77, v63, v63
	v_mov_b32_e32 v79, v0
	v_mov_b32_e32 v81, v77
	v_mul_f32_e32 v0, v55, v55
	v_mul_f32_e32 v82, v64, v64
	v_pk_add_f32 v[78:79], v[78:79], v[80:81]
	v_pk_fma_f32 v[80:81], v[54:55], v[54:55], v[0:1] op_sel_hi:[1,1,0]
	v_mul_f32_e32 v0, v57, v57
	v_mul_f32_e32 v84, v65, v65
	v_mov_b32_e32 v81, v82
	v_pk_fma_f32 v[82:83], v[56:57], v[56:57], v[0:1] op_sel_hi:[1,1,0]
	s_nop 0
	v_mov_b32_e32 v83, v84
	v_pk_add_f32 v[80:81], v[80:81], v[82:83]
	s_nop 0
	v_pk_add_f32 v[78:79], v[78:79], v[80:81]
	s_nop 0
	v_add_f32_e32 v0, v78, v79
	ds_bpermute_b32 v77, v70, v0
	v_lshl_add_u64 v[78:79], v[66:67], 0, s[86:87]
	s_waitcnt lgkmcnt(0)
	v_add_f32_e32 v0, v0, v77
	ds_bpermute_b32 v77, v71, v0
	s_waitcnt lgkmcnt(0)
	v_add_f32_e32 v0, v0, v77
	ds_bpermute_b32 v77, v72, v0
	s_waitcnt lgkmcnt(0)
	v_add_f32_e32 v0, v0, v77
	ds_bpermute_b32 v77, v73, v0
	s_waitcnt lgkmcnt(0)
	v_add_f32_e32 v0, v0, v77
	ds_bpermute_b32 v77, v74, v0
	s_waitcnt lgkmcnt(0)
	v_add_f32_e32 v0, v0, v77
	ds_bpermute_b32 v77, v75, v0
	s_waitcnt lgkmcnt(0)
; __device__ __forceinline__ unsigned pk2(float lo, float hi) { f32x2 v = {lo, hi}; bf16x2_t b = __builtin_convertvector(v, bf16x2_t); return __builtin_bit_cast(unsigned, b); }
; __device__ __forceinline__ void rms_rows(const Ctx& C, const float* __restrict__ x, const float* __restrict__ w, bf16_t* __restrict__ o) {
;     ...
;         const float r = rsqrtf(wave_sum(s) * (1.f / DM) + 1e-6f);
; #pragma unroll
;         for (int j = 0; j < 8; ++j) { u32x2 q; q.x = pk2(v[j].x * r * wv[j].x, v[j].y * r * wv[j].y); q.y = pk2(v[j].z * r * wv[j].z, v[j].w * r * wv[j].w);
;             const int col = 4 * (C.lane + 64 * j);
;             *(u32x2*)(o + ((size_t)((row >> 8) * (DM / 64) + (col >> 6)) * 256 + (row & 255)) * 64 + (col & 63)) = q; }
	v_add_f32_e32 v0, v0, v77
	v_fmamk_f32 v0, v0, 0x3a000000, v196
	v_cmp_gt_f32_e32 vcc, s85, v0
	v_mul_f32_e32 v77, 0x4b800000, v0
	s_nop 0
	v_cndmask_b32_e32 v0, v0, v77, vcc
	v_rsq_f32_e32 v0, v0
	s_nop 0
	v_mul_f32_e32 v77, 0x45800000, v0
	v_cndmask_b32_e32 v0, v0, v77, vcc
	v_pk_mul_f32 v[38:39], v[38:39], v[0:1] op_sel_hi:[1,0]
	v_pk_mul_f32 v[40:41], v[40:41], v[0:1] op_sel_hi:[1,0]
	v_pk_mul_f32 v[38:39], v[30:31], v[38:39]
	v_pk_mul_f32 v[40:41], v[32:33], v[40:41]
	v_pk_mul_f32 v[34:35], v[34:35], v[0:1] op_sel_hi:[1,0]
	v_pk_mul_f32 v[36:37], v[36:37], v[0:1] op_sel_hi:[1,0]
	v_cvt_pk_bf16_f32 v38, v38, v39
	v_cvt_pk_bf16_f32 v39, v40, v41
	v_or_b32_e32 v40, s1, v76
	v_pk_mul_f32 v[34:35], v[26:27], v[34:35]
	v_pk_mul_f32 v[36:37], v[28:29], v[36:37]
	v_cvt_pk_bf16_f32 v34, v34, v35
	v_cvt_pk_bf16_f32 v35, v36, v37
	v_or_b32_e32 v36, 4, v40
	v_ashrrev_i32_e32 v37, 31, v36
	v_lshlrev_b64 v[36:37], 15, v[36:37]
	v_lshl_add_u64 v[36:37], v[78:79], 0, v[36:37]
	global_store_dwordx2 v[36:37], v[34:35], off
	v_pk_mul_f32 v[34:35], v[46:47], v[0:1] op_sel_hi:[1,0]
	v_pk_mul_f32 v[36:37], v[48:49], v[0:1] op_sel_hi:[1,0]
	v_pk_mul_f32 v[34:35], v[22:23], v[34:35]
	v_pk_mul_f32 v[36:37], v[24:25], v[36:37]
	v_cvt_pk_bf16_f32 v34, v34, v35
	v_cvt_pk_bf16_f32 v35, v36, v37
	v_or_b32_e32 v36, 8, v40
	v_ashrrev_i32_e32 v37, 31, v36
	v_lshlrev_b64 v[36:37], 15, v[36:37]
	v_lshl_add_u64 v[36:37], v[78:79], 0, v[36:37]
	global_store_dwordx2 v[36:37], v[34:35], off
	v_pk_mul_f32 v[34:35], v[42:43], v[0:1] op_sel_hi:[1,0]
	v_pk_mul_f32 v[36:37], v[44:45], v[0:1] op_sel_hi:[1,0]
	v_pk_mul_f32 v[34:35], v[18:19], v[34:35]
	v_pk_mul_f32 v[36:37], v[20:21], v[36:37]
	v_cvt_pk_bf16_f32 v34, v34, v35
	v_cvt_pk_bf16_f32 v35, v36, v37
	v_or_b32_e32 v36, 12, v40
	v_ashrrev_i32_e32 v37, 31, v36
	v_lshlrev_b64 v[36:37], 15, v[36:37]
	v_lshl_add_u64 v[36:37], v[78:79], 0, v[36:37]
	global_store_dwordx2 v[36:37], v[34:35], off
	v_pk_mul_f32 v[34:35], v[50:51], v[0:1] op_sel_hi:[1,0]
	v_pk_mul_f32 v[36:37], v[52:53], v[0:1] op_sel_hi:[1,0]
	v_pk_mul_f32 v[34:35], v[14:15], v[34:35]
	v_pk_mul_f32 v[36:37], v[16:17], v[36:37]
	v_cvt_pk_bf16_f32 v34, v34, v35
	v_cvt_pk_bf16_f32 v35, v36, v37
	v_or_b32_e32 v36, 16, v40
	v_ashrrev_i32_e32 v37, 31, v36
	v_lshlrev_b64 v[36:37], 15, v[36:37]
	v_lshl_add_u64 v[36:37], v[78:79], 0, v[36:37]
	global_store_dwordx2 v[36:37], v[34:35], off
	v_pk_mul_f32 v[34:35], v[58:59], v[0:1] op_sel_hi:[1,0]
	v_pk_mul_f32 v[36:37], v[60:61], v[0:1] op_sel_hi:[1,0]
	v_pk_mul_f32 v[34:35], v[10:11], v[34:35]
	v_pk_mul_f32 v[36:37], v[12:13], v[36:37]
	v_cvt_pk_bf16_f32 v34, v34, v35
	v_cvt_pk_bf16_f32 v35, v36, v37
	v_or_b32_e32 v36, 20, v40
	v_ashrrev_i32_e32 v37, 31, v36
	v_lshlrev_b64 v[36:37], 15, v[36:37]
	v_lshl_add_u64 v[36:37], v[78:79], 0, v[36:37]
	global_store_dwordx2 v[36:37], v[34:35], off
	v_pk_mul_f32 v[34:35], v[54:55], v[0:1] op_sel_hi:[1,0]
	v_pk_mul_f32 v[36:37], v[56:57], v[0:1] op_sel_hi:[1,0]
	v_pk_mul_f32 v[34:35], v[6:7], v[34:35]
	v_pk_mul_f32 v[36:37], v[8:9], v[36:37]
	v_cvt_pk_bf16_f32 v34, v34, v35
	v_cvt_pk_bf16_f32 v35, v36, v37
	v_or_b32_e32 v36, 24, v40
	v_ashrrev_i32_e32 v37, 31, v36
	v_lshlrev_b64 v[36:37], 15, v[36:37]
	v_lshl_add_u64 v[36:37], v[78:79], 0, v[36:37]
	global_store_dwordx2 v[36:37], v[34:35], off
	v_pk_mul_f32 v[34:35], v[62:63], v[0:1] op_sel_hi:[1,0]
	v_pk_mul_f32 v[36:37], v[64:65], v[0:1] op_sel_hi:[1,0]
	v_pk_mul_f32 v[34:35], v[2:3], v[34:35]
	v_pk_mul_f32 v[36:37], v[4:5], v[36:37]
	v_cvt_pk_bf16_f32 v34, v34, v35
	v_cvt_pk_bf16_f32 v35, v36, v37
	v_or_b32_e32 v36, 28, v40
	v_ashrrev_i32_e32 v41, 31, v40
	v_ashrrev_i32_e32 v37, 31, v36
	v_lshlrev_b64 v[80:81], 15, v[40:41]
	v_lshlrev_b64 v[36:37], 15, v[36:37]
	v_lshl_add_u64 v[80:81], v[78:79], 0, v[80:81]
	v_lshl_add_u64 v[36:37], v[78:79], 0, v[36:37]
	global_store_dwordx2 v[80:81], v[38:39], off
	global_store_dwordx2 v[36:37], v[34:35], off
	s_cbranch_scc1 .LBB0_1030
